# add: gmlp transposition LDS XOR-swizzle (ds_write_b16 16-way bank conflicts to 2-way)
# baseline (speedup 1.0000x reference)
.LBB0_473:
	s_or_b64 exec, exec, s[66:67]
	v_lshl_add_u32 v158, v105, 2, 0
	s_waitcnt lgkmcnt(0)
	s_barrier
	ds_read_b32 v30, v158 offset:34816
	s_movk_i32 s10, 0x110
	v_mad_u32_u24 v31, v107, s10, 0
	s_waitcnt vmcnt(20)
	v_lshlrev_b32_e32 v107, 16, v26
	v_and_b32_e32 v26, 0xffff0000, v26
	s_waitcnt lgkmcnt(0)
	v_mul_f32_e32 v107, v30, v107
	v_mul_f32_e32 v26, v30, v26
	s_waitcnt vmcnt(15)
	v_mul_f32_e32 v107, v14, v107
	v_mul_f32_e32 v26, v15, v26
	v_cvt_pk_bf16_f32 v26, v107, v26
	v_lshlrev_b32_e32 v107, 16, v27
	v_and_b32_e32 v27, 0xffff0000, v27
	v_mul_f32_e32 v107, v30, v107
	v_mul_f32_e32 v27, v30, v27
	v_mul_f32_e32 v107, v16, v107
	v_mul_f32_e32 v27, v17, v27
	v_cvt_pk_bf16_f32 v27, v107, v27
	v_lshlrev_b32_e32 v107, 16, v28
	v_and_b32_e32 v28, 0xffff0000, v28
	v_mul_f32_e32 v107, v30, v107
	v_mul_f32_e32 v28, v30, v28
	v_mul_f32_e32 v107, v6, v107
	v_mul_f32_e32 v28, v7, v28
	v_cvt_pk_bf16_f32 v28, v107, v28
	v_lshlrev_b32_e32 v107, 16, v29
	v_and_b32_e32 v29, 0xffff0000, v29
	v_mul_f32_e32 v107, v30, v107
	v_mul_f32_e32 v29, v30, v29
	v_lshlrev_b32_e32 v30, 1, v105
	v_mul_f32_e32 v29, v9, v29
	v_mbcnt_lo_u32_b32 v249, -1, 0
	v_mbcnt_hi_u32_b32 v249, -1, v249
	v_and_b32_e32 v244, 7, v249
	v_lshlrev_b32_e32 v244, 4, v244
	v_xad_u32 v155, v30, v244, v31
	v_mul_f32_e32 v107, v8, v107
	v_cvt_pk_bf16_f32 v29, v107, v29
	ds_write_b16 v155, v26
	ds_write_b16_d16_hi v155, v26 offset:272
	ds_write_b16 v155, v27 offset:544
	ds_write_b16_d16_hi v155, v27 offset:816
	ds_write_b16 v155, v28 offset:1088
	v_lshl_add_u32 v159, v87, 2, 0
	ds_read_b32 v26, v159 offset:34816
	v_lshlrev_b32_e32 v27, 16, v22
	v_and_b32_e32 v22, 0xffff0000, v22
	ds_write_b16_d16_hi v155, v28 offset:1360
	ds_write_b16 v155, v29 offset:1632
	ds_write_b16_d16_hi v155, v29 offset:1904
	v_lshl_add_u32 v161, v33, 2, 0
	s_waitcnt lgkmcnt(3)
	v_mul_f32_e32 v27, v26, v27
	v_mul_f32_e32 v22, v26, v22
	v_mul_f32_e32 v27, v14, v27
	v_mul_f32_e32 v22, v15, v22
	v_cvt_pk_bf16_f32 v22, v27, v22
	v_lshlrev_b32_e32 v27, 16, v23
	v_and_b32_e32 v23, 0xffff0000, v23
	v_mul_f32_e32 v27, v26, v27
	v_mul_f32_e32 v23, v26, v23
	v_mul_f32_e32 v27, v16, v27
	v_mul_f32_e32 v23, v17, v23
	v_cvt_pk_bf16_f32 v23, v27, v23
	v_lshlrev_b32_e32 v27, 16, v24
	v_and_b32_e32 v24, 0xffff0000, v24
	v_mul_f32_e32 v27, v26, v27
	v_mul_f32_e32 v24, v26, v24
	v_mul_f32_e32 v27, v6, v27
	v_mul_f32_e32 v24, v7, v24
	v_cvt_pk_bf16_f32 v24, v27, v24
	v_lshlrev_b32_e32 v27, 16, v25
	v_and_b32_e32 v25, 0xffff0000, v25
	v_mul_f32_e32 v27, v26, v27
	v_mul_f32_e32 v25, v26, v25
	v_lshlrev_b32_e32 v26, 1, v87
	v_mul_f32_e32 v25, v9, v25
	v_xad_u32 v156, v26, v244, v31
	v_mul_f32_e32 v27, v8, v27
	v_cvt_pk_bf16_f32 v25, v27, v25
	ds_write_b16 v156, v22
	ds_write_b16_d16_hi v156, v22 offset:272
	ds_write_b16 v156, v23 offset:544
	ds_write_b16_d16_hi v156, v23 offset:816
	ds_write_b16 v156, v24 offset:1088
	ds_read_b32 v22, v161 offset:34816
	v_lshlrev_b32_e32 v23, 16, v18
	v_and_b32_e32 v18, 0xffff0000, v18
	ds_write_b16_d16_hi v156, v24 offset:1360
	ds_write_b16 v156, v25 offset:1632
	ds_write_b16_d16_hi v156, v25 offset:1904
	v_lshl_add_u32 v162, v32, 2, 0
	s_waitcnt lgkmcnt(3)
	v_mul_f32_e32 v23, v22, v23
	v_mul_f32_e32 v18, v22, v18
	v_mul_f32_e32 v23, v14, v23
	v_mul_f32_e32 v18, v15, v18
	v_cvt_pk_bf16_f32 v18, v23, v18
	v_lshlrev_b32_e32 v23, 16, v19
	v_and_b32_e32 v19, 0xffff0000, v19
	v_mul_f32_e32 v23, v22, v23
	v_mul_f32_e32 v19, v22, v19
	v_mul_f32_e32 v23, v16, v23
	v_mul_f32_e32 v19, v17, v19
	v_cvt_pk_bf16_f32 v19, v23, v19
	v_lshlrev_b32_e32 v23, 16, v20
	v_and_b32_e32 v20, 0xffff0000, v20
	v_mul_f32_e32 v23, v22, v23
	v_mul_f32_e32 v20, v22, v20
	v_mul_f32_e32 v23, v6, v23
	v_mul_f32_e32 v20, v7, v20
	v_cvt_pk_bf16_f32 v20, v23, v20
	v_lshlrev_b32_e32 v23, 16, v21
	v_and_b32_e32 v21, 0xffff0000, v21
	v_mul_f32_e32 v23, v22, v23
	v_mul_f32_e32 v21, v22, v21
	v_lshlrev_b32_e32 v22, 1, v33
	v_mul_f32_e32 v21, v9, v21
	v_xad_u32 v157, v22, v244, v31
	v_mul_f32_e32 v23, v8, v23
	v_cvt_pk_bf16_f32 v21, v23, v21
	ds_write_b16 v157, v18
	ds_write_b16_d16_hi v157, v18 offset:272
	ds_write_b16 v157, v19 offset:544
	ds_write_b16_d16_hi v157, v19 offset:816
	ds_write_b16 v157, v20 offset:1088
	ds_read_b32 v18, v162 offset:34816
	v_lshlrev_b32_e32 v19, 16, v2
	v_and_b32_e32 v2, 0xffff0000, v2
	ds_write_b16_d16_hi v157, v20 offset:1360
	ds_write_b16 v157, v21 offset:1632
	ds_write_b16_d16_hi v157, v21 offset:1904
	s_and_b64 vcc, exec, s[8:9]
	s_waitcnt lgkmcnt(3)
	v_mul_f32_e32 v19, v18, v19
	v_mul_f32_e32 v2, v18, v2
	v_mul_f32_e32 v14, v14, v19
	v_mul_f32_e32 v2, v15, v2
	v_cvt_pk_bf16_f32 v2, v14, v2
	v_lshlrev_b32_e32 v14, 16, v3
	v_and_b32_e32 v3, 0xffff0000, v3
	v_mul_f32_e32 v14, v18, v14
	v_mul_f32_e32 v3, v18, v3
	v_mul_f32_e32 v14, v16, v14
	v_mul_f32_e32 v3, v17, v3
	v_cvt_pk_bf16_f32 v3, v14, v3
	v_lshlrev_b32_e32 v14, 16, v4
	v_and_b32_e32 v4, 0xffff0000, v4
	v_mul_f32_e32 v14, v18, v14
	v_mul_f32_e32 v4, v18, v4
	v_mul_f32_e32 v6, v6, v14
	v_mul_f32_e32 v4, v7, v4
	v_cvt_pk_bf16_f32 v4, v6, v4
	v_lshlrev_b32_e32 v6, 16, v5
	v_and_b32_e32 v5, 0xffff0000, v5
	v_mul_f32_e32 v6, v18, v6
	v_mul_f32_e32 v5, v18, v5
	v_mul_f32_e32 v6, v8, v6
	v_mul_f32_e32 v5, v9, v5
	v_cvt_pk_bf16_f32 v5, v6, v5
	v_lshlrev_b32_e32 v6, 1, v32
	v_xad_u32 v160, v6, v244, v31
	ds_write_b16 v160, v2
	ds_write_b16_d16_hi v160, v2 offset:272
	ds_write_b16 v160, v3 offset:544
	ds_write_b16_d16_hi v160, v3 offset:816
	ds_write_b16 v160, v4 offset:1088
	ds_write_b16_d16_hi v160, v4 offset:1360
	ds_write_b16 v160, v5 offset:1632
	ds_write_b16_d16_hi v160, v5 offset:1904
	v_or_b32_e32 v2, s20, v130
	v_or_b32_e32 v3, s20, v132
	v_mad_u32_u24 v2, v2, s10, 0
	v_mad_u32_u24 v3, v3, s10, 0
	v_add_u32_e32 v153, v3, v131
	v_add_u32_e32 v154, v2, v131
	v_bfe_u32 v250, v249, 3, 1
	v_bfe_u32 v251, v249, 5, 1
	v_lshlrev_b32_e32 v251, 5, v251
	v_sub_u32_e32 v251, 16, v251
	v_mul_i32_i24_e32 v250, v250, v251
	v_bfe_u32 v251, v249, 4, 1
	v_lshlrev_b32_e32 v251, 5, v251
	v_add_u32_e32 v245, v154, v250
	v_add_u32_e32 v247, v153, v250
	v_sub_u32_e32 v246, v245, v251
	v_sub_u32_e32 v248, v247, v251
	v_add_u32_e32 v245, v245, v251
	v_add_u32_e32 v247, v247, v251
	s_waitcnt lgkmcnt(0)
	s_barrier
	s_cbranch_vccnz .LBB0_497
	ds_read_b128 v[2:5], v245
	ds_read_b128 v[6:9], v247 offset:64
	s_waitcnt vmcnt(9) lgkmcnt(1)
	v_mfma_f32_32x32x16_bf16 v[18:33], v[2:5], v[10:13], 0
	s_waitcnt lgkmcnt(0)
	v_mfma_f32_32x32x16_bf16 v[2:17], v[6:9], v[10:13], 0
	s_and_b64 vcc, exec, s[8:9]
	s_cbranch_vccnz .LBB0_476
.LBB0_475:
	ds_read_b128 v[130:133], v246 offset:32
	s_waitcnt lgkmcnt(0)
	v_mfma_f32_32x32x16_bf16 v[18:33], v[130:133], v[82:85], v[18:33]
	ds_read_b128 v[130:133], v248 offset:96
	s_waitcnt lgkmcnt(0)
	v_mfma_f32_32x32x16_bf16 v[2:17], v[130:133], v[82:85], v[2:17]
.LBB0_476:
	s_and_b64 vcc, exec, s[6:7]
	s_cbranch_vccnz .LBB0_482
	ds_read_b128 v[82:85], v245 offset:64
	s_waitcnt lgkmcnt(0)
	v_mfma_f32_32x32x16_bf16 v[18:33], v[82:85], v[78:81], v[18:33]
	ds_read_b128 v[82:85], v247
	s_waitcnt lgkmcnt(0)
	v_mfma_f32_32x32x16_bf16 v[2:17], v[82:85], v[78:81], v[2:17]
	s_and_b64 vcc, exec, s[6:7]
	s_cbranch_vccz .LBB0_483

.LBB0_479:
	ds_read_b128 v[74:77], v245 offset:128
	s_waitcnt lgkmcnt(0)
	v_mfma_f32_32x32x16_bf16 v[18:33], v[74:77], v[70:73], v[18:33]
	ds_read_b128 v[74:77], v247 offset:192
	s_waitcnt lgkmcnt(0)
	v_mfma_f32_32x32x16_bf16 v[2:17], v[74:77], v[70:73], v[2:17]
	s_and_b64 vcc, exec, s[4:5]
	s_cbranch_vccz .LBB0_485

.LBB0_481:
	ds_read_b128 v[66:69], v245 offset:192
	s_waitcnt lgkmcnt(0)
	v_mfma_f32_32x32x16_bf16 v[18:33], v[66:69], v[62:65], v[18:33]
	ds_read_b128 v[66:69], v247 offset:128
	s_waitcnt lgkmcnt(0)
	v_mfma_f32_32x32x16_bf16 v[2:17], v[66:69], v[62:65], v[2:17]
	s_and_b64 vcc, exec, s[0:1]
	s_cbranch_vccz .LBB0_487
	s_branch .LBB0_488

.LBB0_483:
	ds_read_b128 v[78:81], v246 offset:96
	s_waitcnt lgkmcnt(0)
	v_mfma_f32_32x32x16_bf16 v[18:33], v[78:81], v[74:77], v[18:33]
	ds_read_b128 v[78:81], v248 offset:32
	s_waitcnt lgkmcnt(0)
	v_mfma_f32_32x32x16_bf16 v[2:17], v[78:81], v[74:77], v[2:17]
	s_and_b64 vcc, exec, s[4:5]
	s_cbranch_vccz .LBB0_479

.LBB0_485:
	ds_read_b128 v[70:73], v246 offset:160
	s_waitcnt lgkmcnt(0)
	v_mfma_f32_32x32x16_bf16 v[18:33], v[70:73], v[66:69], v[18:33]
	ds_read_b128 v[70:73], v248 offset:224
	s_waitcnt lgkmcnt(0)
	v_mfma_f32_32x32x16_bf16 v[2:17], v[70:73], v[66:69], v[2:17]
	s_and_b64 vcc, exec, s[0:1]
	s_cbranch_vccz .LBB0_481

.LBB0_487:
	ds_read_b128 v[62:65], v246 offset:224
	s_waitcnt lgkmcnt(0)
	v_mfma_f32_32x32x16_bf16 v[18:33], v[62:65], v[58:61], v[18:33]
	ds_read_b128 v[62:65], v248 offset:160
	s_waitcnt lgkmcnt(0)
	v_mfma_f32_32x32x16_bf16 v[2:17], v[62:65], v[58:61], v[2:17]

.LBB0_506:
	v_lshl_add_u64 v[128:129], v[128:129], 0, v[0:1]
	s_mov_b32 s2, s22
	s_mov_b32 s3, s87
	s_mov_b32 s65, s87
	v_lshl_add_u64 v[6:7], v[128:129], 0, s[2:3]
	v_lshl_add_u64 v[132:133], v[128:129], 0, s[64:65]
	v_lshl_add_u64 v[8:9], v[132:133], 0, s[2:3]
	v_lshl_add_u64 v[6:7], v[6:7], 0, s[64:65]
	global_load_dword v113, v[116:117], off offset:512
	global_load_dwordx2 v[150:151], v[8:9], off
	global_load_dwordx2 v[148:149], v[8:9], off offset:16
	global_load_dwordx2 v[146:147], v[8:9], off offset:32
	global_load_dwordx2 v[144:145], v[8:9], off offset:48
	ds_read_b32 v0, v158 offset:34816
	global_load_dwordx2 v[142:143], v[6:7], off offset:64
	global_load_dwordx2 v[140:141], v[6:7], off offset:80
	global_load_dwordx2 v[138:139], v[6:7], off offset:96
	global_load_dwordx2 v[136:137], v[6:7], off offset:112
	v_lshlrev_b32_e32 v6, 16, v54
	v_and_b32_e32 v7, 0xffff0000, v54
	v_and_b32_e32 v8, 0xffff0000, v55
	s_waitcnt lgkmcnt(0)
	v_mul_f32_e32 v6, v0, v6
	v_mul_f32_e32 v7, v0, v7
	v_mul_f32_e32 v6, v42, v6
	v_mul_f32_e32 v7, v43, v7
	v_cvt_pk_bf16_f32 v6, v6, v7
	v_lshlrev_b32_e32 v7, 16, v55
	v_mul_f32_e32 v7, v0, v7
	v_mul_f32_e32 v8, v0, v8
	v_mul_f32_e32 v7, v44, v7
	v_mul_f32_e32 v8, v45, v8
	v_cvt_pk_bf16_f32 v7, v7, v8
	v_lshlrev_b32_e32 v8, 16, v56
	v_and_b32_e32 v9, 0xffff0000, v56
	v_mul_f32_e32 v8, v0, v8
	v_mul_f32_e32 v9, v0, v9
	v_mul_f32_e32 v8, v34, v8
	v_mul_f32_e32 v9, v35, v9
	v_cvt_pk_bf16_f32 v8, v8, v9
	v_lshlrev_b32_e32 v9, 16, v57
	v_and_b32_e32 v10, 0xffff0000, v57
	v_mul_f32_e32 v9, v0, v9
	v_mul_f32_e32 v0, v0, v10
	v_mul_f32_e32 v0, v37, v0
	v_mul_f32_e32 v9, v36, v9
	v_cvt_pk_bf16_f32 v0, v9, v0
	ds_write_b16 v155, v6
	ds_write_b16_d16_hi v155, v6 offset:272
	ds_write_b16 v155, v7 offset:544
	ds_write_b16_d16_hi v155, v7 offset:816
	ds_write_b16 v155, v8 offset:1088
	ds_read_b32 v6, v159 offset:34816
	ds_write_b16_d16_hi v155, v8 offset:1360
	ds_write_b16 v155, v0 offset:1632
	ds_write_b16_d16_hi v155, v0 offset:1904
	v_lshlrev_b32_e32 v0, 16, v50
	v_and_b32_e32 v7, 0xffff0000, v50
	v_and_b32_e32 v8, 0xffff0000, v51
	s_waitcnt lgkmcnt(3)
	v_mul_f32_e32 v0, v6, v0
	v_mul_f32_e32 v7, v6, v7
	v_mul_f32_e32 v0, v42, v0
	v_mul_f32_e32 v7, v43, v7
	v_cvt_pk_bf16_f32 v0, v0, v7
	v_lshlrev_b32_e32 v7, 16, v51
	v_mul_f32_e32 v7, v6, v7
	v_mul_f32_e32 v8, v6, v8
	v_mul_f32_e32 v7, v44, v7
	v_mul_f32_e32 v8, v45, v8
	v_cvt_pk_bf16_f32 v7, v7, v8
	v_lshlrev_b32_e32 v8, 16, v52
	v_and_b32_e32 v9, 0xffff0000, v52
	v_mul_f32_e32 v8, v6, v8
	v_mul_f32_e32 v9, v6, v9
	v_mul_f32_e32 v8, v34, v8
	v_mul_f32_e32 v9, v35, v9
	v_cvt_pk_bf16_f32 v8, v8, v9
	v_lshlrev_b32_e32 v9, 16, v53
	v_and_b32_e32 v10, 0xffff0000, v53
	v_mul_f32_e32 v9, v6, v9
	v_mul_f32_e32 v6, v6, v10
	v_mul_f32_e32 v6, v37, v6
	v_mul_f32_e32 v9, v36, v9
	v_cvt_pk_bf16_f32 v6, v9, v6
	ds_write_b16 v156, v0
	ds_write_b16_d16_hi v156, v0 offset:272
	ds_write_b16 v156, v7 offset:544
	ds_write_b16_d16_hi v156, v7 offset:816
	ds_write_b16 v156, v8 offset:1088
	ds_read_b32 v0, v161 offset:34816
	ds_write_b16_d16_hi v156, v8 offset:1360
	ds_write_b16 v156, v6 offset:1632
	ds_write_b16_d16_hi v156, v6 offset:1904
	v_lshlrev_b32_e32 v6, 16, v46
	v_and_b32_e32 v7, 0xffff0000, v46
	v_and_b32_e32 v8, 0xffff0000, v47
	s_waitcnt lgkmcnt(3)
	v_mul_f32_e32 v6, v0, v6
	v_mul_f32_e32 v7, v0, v7
	v_mul_f32_e32 v6, v42, v6
	v_mul_f32_e32 v7, v43, v7
	v_cvt_pk_bf16_f32 v6, v6, v7
	v_lshlrev_b32_e32 v7, 16, v47
	v_mul_f32_e32 v7, v0, v7
	v_mul_f32_e32 v8, v0, v8
	v_mul_f32_e32 v7, v44, v7
	v_mul_f32_e32 v8, v45, v8
	v_cvt_pk_bf16_f32 v7, v7, v8
	v_lshlrev_b32_e32 v8, 16, v48
	v_and_b32_e32 v9, 0xffff0000, v48
	v_mul_f32_e32 v8, v0, v8
	v_mul_f32_e32 v9, v0, v9
	v_mul_f32_e32 v8, v34, v8
	v_mul_f32_e32 v9, v35, v9
	v_cvt_pk_bf16_f32 v8, v8, v9
	v_lshlrev_b32_e32 v9, 16, v49
	v_and_b32_e32 v10, 0xffff0000, v49
	v_mul_f32_e32 v9, v0, v9
	v_mul_f32_e32 v0, v0, v10
	v_mul_f32_e32 v0, v37, v0
	v_mul_f32_e32 v9, v36, v9
	v_cvt_pk_bf16_f32 v0, v9, v0
	ds_write_b16 v157, v6
	ds_write_b16_d16_hi v157, v6 offset:272
	ds_write_b16 v157, v7 offset:544
	ds_write_b16_d16_hi v157, v7 offset:816
	ds_write_b16 v157, v8 offset:1088
	ds_read_b32 v6, v162 offset:34816
	ds_write_b16_d16_hi v157, v8 offset:1360
	ds_write_b16 v157, v0 offset:1632
	ds_write_b16_d16_hi v157, v0 offset:1904
	v_lshlrev_b32_e32 v0, 16, v38
	v_and_b32_e32 v7, 0xffff0000, v38
	v_and_b32_e32 v8, 0xffff0000, v39
	s_waitcnt lgkmcnt(3)
	v_mul_f32_e32 v0, v6, v0
	v_mul_f32_e32 v7, v6, v7
	v_mul_f32_e32 v0, v42, v0
	v_mul_f32_e32 v7, v43, v7
	v_cvt_pk_bf16_f32 v0, v0, v7
	v_lshlrev_b32_e32 v7, 16, v39
	v_mul_f32_e32 v7, v6, v7
	v_mul_f32_e32 v8, v6, v8
	v_mul_f32_e32 v7, v44, v7
	v_mul_f32_e32 v8, v45, v8
	v_cvt_pk_bf16_f32 v7, v7, v8
	v_lshlrev_b32_e32 v8, 16, v40
	v_and_b32_e32 v9, 0xffff0000, v40
	v_mul_f32_e32 v8, v6, v8
	v_mul_f32_e32 v9, v6, v9
	v_mul_f32_e32 v8, v34, v8
	v_mul_f32_e32 v9, v35, v9
	v_cvt_pk_bf16_f32 v8, v8, v9
	v_lshlrev_b32_e32 v9, 16, v41
	v_and_b32_e32 v10, 0xffff0000, v41
	v_mul_f32_e32 v9, v6, v9
	v_mul_f32_e32 v6, v6, v10
	s_mov_b32 s10, s22
	v_mul_f32_e32 v6, v37, v6
	s_and_b64 vcc, exec, s[8:9]
	v_mul_f32_e32 v9, v36, v9
	v_cvt_pk_bf16_f32 v6, v9, v6
	ds_write_b16 v160, v0
	ds_write_b16_d16_hi v160, v0 offset:272
	ds_write_b16 v160, v7 offset:544
	ds_write_b16_d16_hi v160, v7 offset:816
	ds_write_b16 v160, v8 offset:1088
	ds_write_b16_d16_hi v160, v8 offset:1360
	ds_write_b16 v160, v6 offset:1632
	ds_write_b16_d16_hi v160, v6 offset:1904
	s_waitcnt lgkmcnt(0)
	s_barrier
	s_cbranch_vccnz .LBB0_530
	ds_read_b128 v[6:9], v245
	ds_read_b128 v[10:13], v247 offset:64
	s_waitcnt vmcnt(9) lgkmcnt(1)
	v_mfma_f32_32x32x16_bf16 v[18:33], v[6:9], v[2:5], 0
	s_waitcnt lgkmcnt(0)
	v_mfma_f32_32x32x16_bf16 v[2:17], v[10:13], v[2:5], 0
	s_and_b64 vcc, exec, s[8:9]
	s_cbranch_vccnz .LBB0_509
.LBB0_508:
	ds_read_b128 v[34:37], v246 offset:32
	s_waitcnt lgkmcnt(0)
	v_mfma_f32_32x32x16_bf16 v[18:33], v[34:37], v[106:109], v[18:33]
	ds_read_b128 v[34:37], v248 offset:96
	s_waitcnt lgkmcnt(0)
	v_mfma_f32_32x32x16_bf16 v[2:17], v[34:37], v[106:109], v[2:17]
.LBB0_509:
	s_and_b64 vcc, exec, s[6:7]
	s_cbranch_vccnz .LBB0_515
	ds_read_b128 v[34:37], v245 offset:64
	s_waitcnt lgkmcnt(0)
	v_mfma_f32_32x32x16_bf16 v[18:33], v[34:37], v[102:105], v[18:33]
	ds_read_b128 v[34:37], v247
	s_waitcnt lgkmcnt(0)
	v_mfma_f32_32x32x16_bf16 v[2:17], v[34:37], v[102:105], v[2:17]
	s_and_b64 vcc, exec, s[6:7]
	s_cbranch_vccz .LBB0_516

.LBB0_512:
	ds_read_b128 v[34:37], v245 offset:128
	s_waitcnt lgkmcnt(0)
	v_mfma_f32_32x32x16_bf16 v[18:33], v[34:37], v[94:97], v[18:33]
	ds_read_b128 v[34:37], v247 offset:192
	s_waitcnt lgkmcnt(0)
	v_mfma_f32_32x32x16_bf16 v[2:17], v[34:37], v[94:97], v[2:17]
	s_and_b64 vcc, exec, s[4:5]
	s_cbranch_vccz .LBB0_518

.LBB0_514:
	ds_read_b128 v[34:37], v245 offset:192
	s_waitcnt lgkmcnt(0)
	v_mfma_f32_32x32x16_bf16 v[18:33], v[34:37], v[86:89], v[18:33]
	ds_read_b128 v[34:37], v247 offset:128
	s_waitcnt lgkmcnt(0)
	v_mfma_f32_32x32x16_bf16 v[2:17], v[34:37], v[86:89], v[2:17]
	s_and_b64 vcc, exec, s[0:1]
	s_cbranch_vccz .LBB0_520
	s_branch .LBB0_521

.LBB0_516:
	ds_read_b128 v[34:37], v246 offset:96
	s_waitcnt lgkmcnt(0)
	v_mfma_f32_32x32x16_bf16 v[18:33], v[34:37], v[98:101], v[18:33]
	ds_read_b128 v[34:37], v248 offset:32
	s_waitcnt lgkmcnt(0)
	v_mfma_f32_32x32x16_bf16 v[2:17], v[34:37], v[98:101], v[2:17]
	s_and_b64 vcc, exec, s[4:5]
	s_cbranch_vccz .LBB0_512

.LBB0_518:
	ds_read_b128 v[34:37], v246 offset:160
	s_waitcnt lgkmcnt(0)
	v_mfma_f32_32x32x16_bf16 v[18:33], v[34:37], v[90:93], v[18:33]
	ds_read_b128 v[34:37], v248 offset:224
	s_waitcnt lgkmcnt(0)
	v_mfma_f32_32x32x16_bf16 v[2:17], v[34:37], v[90:93], v[2:17]
	s_and_b64 vcc, exec, s[0:1]
	s_cbranch_vccz .LBB0_514

.LBB0_520:
	ds_read_b128 v[34:37], v246 offset:224
	s_waitcnt lgkmcnt(0)
	v_mfma_f32_32x32x16_bf16 v[18:33], v[34:37], v[82:85], v[18:33]
	ds_read_b128 v[34:37], v248 offset:160
	s_waitcnt lgkmcnt(0)
	v_mfma_f32_32x32x16_bf16 v[2:17], v[34:37], v[82:85], v[2:17]

.LBB0_539:
	s_mov_b32 s2, s20
	s_mov_b32 s3, s87
	v_lshl_add_u64 v[6:7], v[128:129], 0, s[2:3]
	s_mov_b32 s65, s87
	v_lshl_add_u64 v[8:9], v[132:133], 0, s[2:3]
	v_lshl_add_u64 v[6:7], v[6:7], 0, s[64:65]
	global_load_dword v113, v[116:117], off offset:1024
	global_load_dwordx2 v[140:141], v[8:9], off
	global_load_dwordx2 v[138:139], v[8:9], off offset:16
	global_load_dwordx2 v[136:137], v[8:9], off offset:32
	global_load_dwordx2 v[134:135], v[8:9], off offset:48
	ds_read_b32 v0, v158 offset:34816
	global_load_dwordx2 v[126:127], v[6:7], off offset:64
	global_load_dwordx2 v[124:125], v[6:7], off offset:80
	global_load_dwordx2 v[122:123], v[6:7], off offset:96
	global_load_dwordx2 v[120:121], v[6:7], off offset:112
	v_lshlrev_b32_e32 v6, 16, v78
	v_and_b32_e32 v7, 0xffff0000, v78
	v_and_b32_e32 v8, 0xffff0000, v79
	s_waitcnt lgkmcnt(0)
	v_mul_f32_e32 v6, v0, v6
	v_mul_f32_e32 v7, v0, v7
	v_mul_f32_e32 v6, v66, v6
	v_mul_f32_e32 v7, v67, v7
	v_cvt_pk_bf16_f32 v6, v6, v7
	v_lshlrev_b32_e32 v7, 16, v79
	v_mul_f32_e32 v7, v0, v7
	v_mul_f32_e32 v8, v0, v8
	v_mul_f32_e32 v7, v68, v7
	v_mul_f32_e32 v8, v69, v8
	v_cvt_pk_bf16_f32 v7, v7, v8
	v_lshlrev_b32_e32 v8, 16, v80
	v_and_b32_e32 v9, 0xffff0000, v80
	v_mul_f32_e32 v8, v0, v8
	v_mul_f32_e32 v9, v0, v9
	v_mul_f32_e32 v8, v58, v8
	v_mul_f32_e32 v9, v59, v9
	v_cvt_pk_bf16_f32 v8, v8, v9
	v_lshlrev_b32_e32 v9, 16, v81
	v_and_b32_e32 v10, 0xffff0000, v81
	v_mul_f32_e32 v9, v0, v9
	v_mul_f32_e32 v0, v0, v10
	v_mul_f32_e32 v0, v61, v0
	v_mul_f32_e32 v9, v60, v9
	v_cvt_pk_bf16_f32 v0, v9, v0
	ds_write_b16 v155, v6
	ds_write_b16_d16_hi v155, v6 offset:272
	ds_write_b16 v155, v7 offset:544
	ds_write_b16_d16_hi v155, v7 offset:816
	ds_write_b16 v155, v8 offset:1088
	ds_read_b32 v6, v159 offset:34816
	ds_write_b16_d16_hi v155, v8 offset:1360
	ds_write_b16 v155, v0 offset:1632
	ds_write_b16_d16_hi v155, v0 offset:1904
	v_lshlrev_b32_e32 v0, 16, v74
	v_and_b32_e32 v7, 0xffff0000, v74
	v_and_b32_e32 v8, 0xffff0000, v75
	s_waitcnt lgkmcnt(3)
	v_mul_f32_e32 v0, v6, v0
	v_mul_f32_e32 v7, v6, v7
	v_mul_f32_e32 v0, v66, v0
	v_mul_f32_e32 v7, v67, v7
	v_cvt_pk_bf16_f32 v0, v0, v7
	v_lshlrev_b32_e32 v7, 16, v75
	v_mul_f32_e32 v7, v6, v7
	v_mul_f32_e32 v8, v6, v8
	v_mul_f32_e32 v7, v68, v7
	v_mul_f32_e32 v8, v69, v8
	v_cvt_pk_bf16_f32 v7, v7, v8
	v_lshlrev_b32_e32 v8, 16, v76
	v_and_b32_e32 v9, 0xffff0000, v76
	v_mul_f32_e32 v8, v6, v8
	v_mul_f32_e32 v9, v6, v9
	v_mul_f32_e32 v8, v58, v8
	v_mul_f32_e32 v9, v59, v9
	v_cvt_pk_bf16_f32 v8, v8, v9
	v_lshlrev_b32_e32 v9, 16, v77
	v_and_b32_e32 v10, 0xffff0000, v77
	v_mul_f32_e32 v9, v6, v9
	v_mul_f32_e32 v6, v6, v10
	v_mul_f32_e32 v6, v61, v6
	v_mul_f32_e32 v9, v60, v9
	v_cvt_pk_bf16_f32 v6, v9, v6
	ds_write_b16 v156, v0
	ds_write_b16_d16_hi v156, v0 offset:272
	ds_write_b16 v156, v7 offset:544
	ds_write_b16_d16_hi v156, v7 offset:816
	ds_write_b16 v156, v8 offset:1088
	ds_read_b32 v0, v161 offset:34816
	ds_write_b16_d16_hi v156, v8 offset:1360
	ds_write_b16 v156, v6 offset:1632
	ds_write_b16_d16_hi v156, v6 offset:1904
	v_lshlrev_b32_e32 v6, 16, v70
	v_and_b32_e32 v7, 0xffff0000, v70
	v_and_b32_e32 v8, 0xffff0000, v71
	s_waitcnt lgkmcnt(3)
	v_mul_f32_e32 v6, v0, v6
	v_mul_f32_e32 v7, v0, v7
	v_mul_f32_e32 v6, v66, v6
	v_mul_f32_e32 v7, v67, v7
	v_cvt_pk_bf16_f32 v6, v6, v7
	v_lshlrev_b32_e32 v7, 16, v71
	v_mul_f32_e32 v7, v0, v7
	v_mul_f32_e32 v8, v0, v8
	v_mul_f32_e32 v7, v68, v7
	v_mul_f32_e32 v8, v69, v8
	v_cvt_pk_bf16_f32 v7, v7, v8
	v_lshlrev_b32_e32 v8, 16, v72
	v_and_b32_e32 v9, 0xffff0000, v72
	v_mul_f32_e32 v8, v0, v8
	v_mul_f32_e32 v9, v0, v9
	v_mul_f32_e32 v8, v58, v8
	v_mul_f32_e32 v9, v59, v9
	v_cvt_pk_bf16_f32 v8, v8, v9
	v_lshlrev_b32_e32 v9, 16, v73
	v_and_b32_e32 v10, 0xffff0000, v73
	v_mul_f32_e32 v9, v0, v9
	v_mul_f32_e32 v0, v0, v10
	v_mul_f32_e32 v0, v61, v0
	v_mul_f32_e32 v9, v60, v9
	v_cvt_pk_bf16_f32 v0, v9, v0
	ds_write_b16 v157, v6
	ds_write_b16_d16_hi v157, v6 offset:272
	ds_write_b16 v157, v7 offset:544
	ds_write_b16_d16_hi v157, v7 offset:816
	ds_write_b16 v157, v8 offset:1088
	ds_read_b32 v6, v162 offset:34816
	ds_write_b16_d16_hi v157, v8 offset:1360
	ds_write_b16 v157, v0 offset:1632
	ds_write_b16_d16_hi v157, v0 offset:1904
	v_lshlrev_b32_e32 v0, 16, v62
	v_and_b32_e32 v7, 0xffff0000, v62
	v_and_b32_e32 v8, 0xffff0000, v63
	s_waitcnt lgkmcnt(3)
	v_mul_f32_e32 v0, v6, v0
	v_mul_f32_e32 v7, v6, v7
	v_mul_f32_e32 v0, v66, v0
	v_mul_f32_e32 v7, v67, v7
	v_cvt_pk_bf16_f32 v0, v0, v7
	v_lshlrev_b32_e32 v7, 16, v63
	v_mul_f32_e32 v7, v6, v7
	v_mul_f32_e32 v8, v6, v8
	v_mul_f32_e32 v7, v68, v7
	v_mul_f32_e32 v8, v69, v8
	v_cvt_pk_bf16_f32 v7, v7, v8
	v_lshlrev_b32_e32 v8, 16, v64
	v_and_b32_e32 v9, 0xffff0000, v64
	v_mul_f32_e32 v8, v6, v8
	v_mul_f32_e32 v9, v6, v9
	v_mul_f32_e32 v8, v58, v8
	v_mul_f32_e32 v9, v59, v9
	v_cvt_pk_bf16_f32 v8, v8, v9
	v_lshlrev_b32_e32 v9, 16, v65
	v_and_b32_e32 v10, 0xffff0000, v65
	v_mul_f32_e32 v9, v6, v9
	v_mul_f32_e32 v6, v6, v10
	s_mov_b32 s10, s20
	v_mul_f32_e32 v6, v61, v6
	s_and_b64 vcc, exec, s[8:9]
	v_mul_f32_e32 v9, v60, v9
	v_cvt_pk_bf16_f32 v6, v9, v6
	ds_write_b16 v160, v0
	ds_write_b16_d16_hi v160, v0 offset:272
	ds_write_b16 v160, v7 offset:544
	ds_write_b16_d16_hi v160, v7 offset:816
	ds_write_b16 v160, v8 offset:1088
	ds_write_b16_d16_hi v160, v8 offset:1360
	ds_write_b16 v160, v6 offset:1632
	ds_write_b16_d16_hi v160, v6 offset:1904
	s_waitcnt lgkmcnt(0)
	s_barrier
	s_cbranch_vccnz .LBB0_563
	ds_read_b128 v[6:9], v245
	ds_read_b128 v[10:13], v247 offset:64
	s_waitcnt vmcnt(9) lgkmcnt(1)
	v_mfma_f32_32x32x16_bf16 v[18:33], v[6:9], v[2:5], 0
	s_waitcnt lgkmcnt(0)
	v_mfma_f32_32x32x16_bf16 v[2:17], v[10:13], v[2:5], 0
	s_and_b64 vcc, exec, s[8:9]
	s_cbranch_vccnz .LBB0_542
.LBB0_541:
	ds_read_b128 v[58:61], v246 offset:32
	s_waitcnt lgkmcnt(0)
	v_mfma_f32_32x32x16_bf16 v[18:33], v[58:61], v[106:109], v[18:33]
	ds_read_b128 v[58:61], v248 offset:96
	s_waitcnt lgkmcnt(0)
	v_mfma_f32_32x32x16_bf16 v[2:17], v[58:61], v[106:109], v[2:17]
.LBB0_542:
	s_and_b64 vcc, exec, s[6:7]
	s_cbranch_vccnz .LBB0_548
	ds_read_b128 v[58:61], v245 offset:64
	s_waitcnt lgkmcnt(0)
	v_mfma_f32_32x32x16_bf16 v[18:33], v[58:61], v[102:105], v[18:33]
	ds_read_b128 v[58:61], v247
	s_waitcnt lgkmcnt(0)
	v_mfma_f32_32x32x16_bf16 v[2:17], v[58:61], v[102:105], v[2:17]
	s_and_b64 vcc, exec, s[6:7]
	s_cbranch_vccz .LBB0_549

.LBB0_545:
	ds_read_b128 v[58:61], v245 offset:128
	s_waitcnt lgkmcnt(0)
	v_mfma_f32_32x32x16_bf16 v[18:33], v[58:61], v[94:97], v[18:33]
	ds_read_b128 v[58:61], v247 offset:192
	s_waitcnt lgkmcnt(0)
	v_mfma_f32_32x32x16_bf16 v[2:17], v[58:61], v[94:97], v[2:17]
	s_and_b64 vcc, exec, s[4:5]
	s_cbranch_vccz .LBB0_551

.LBB0_547:
	ds_read_b128 v[58:61], v245 offset:192
	s_waitcnt lgkmcnt(0)
	v_mfma_f32_32x32x16_bf16 v[18:33], v[58:61], v[86:89], v[18:33]
	ds_read_b128 v[58:61], v247 offset:128
	s_waitcnt lgkmcnt(0)
	v_mfma_f32_32x32x16_bf16 v[2:17], v[58:61], v[86:89], v[2:17]
	s_and_b64 vcc, exec, s[0:1]
	s_cbranch_vccz .LBB0_553
	s_branch .LBB0_554

.LBB0_549:
	ds_read_b128 v[58:61], v246 offset:96
	s_waitcnt lgkmcnt(0)
	v_mfma_f32_32x32x16_bf16 v[18:33], v[58:61], v[98:101], v[18:33]
	ds_read_b128 v[58:61], v248 offset:32
	s_waitcnt lgkmcnt(0)
	v_mfma_f32_32x32x16_bf16 v[2:17], v[58:61], v[98:101], v[2:17]
	s_and_b64 vcc, exec, s[4:5]
	s_cbranch_vccz .LBB0_545

.LBB0_551:
	ds_read_b128 v[58:61], v246 offset:160
	s_waitcnt lgkmcnt(0)
	v_mfma_f32_32x32x16_bf16 v[18:33], v[58:61], v[90:93], v[18:33]
	ds_read_b128 v[58:61], v248 offset:224
	s_waitcnt lgkmcnt(0)
	v_mfma_f32_32x32x16_bf16 v[2:17], v[58:61], v[90:93], v[2:17]
	s_and_b64 vcc, exec, s[0:1]
	s_cbranch_vccz .LBB0_547

.LBB0_553:
	ds_read_b128 v[58:61], v246 offset:224
	s_waitcnt lgkmcnt(0)
	v_mfma_f32_32x32x16_bf16 v[18:33], v[58:61], v[82:85], v[18:33]
	ds_read_b128 v[58:61], v248 offset:160
	s_waitcnt lgkmcnt(0)
	v_mfma_f32_32x32x16_bf16 v[2:17], v[58:61], v[82:85], v[2:17]

.LBB0_572:
	s_mov_b32 s2, s22
	s_mov_b32 s3, s87
	v_lshl_add_u64 v[6:7], v[128:129], 0, s[2:3]
	s_mov_b32 s65, s87
	v_lshl_add_u64 v[8:9], v[132:133], 0, s[2:3]
	v_lshl_add_u64 v[6:7], v[6:7], 0, s[64:65]
	global_load_dword v102, v[116:117], off offset:1536
	global_load_dwordx2 v[100:101], v[8:9], off
	global_load_dwordx2 v[98:99], v[8:9], off offset:16
	global_load_dwordx2 v[96:97], v[8:9], off offset:32
	global_load_dwordx2 v[94:95], v[8:9], off offset:48
	ds_read_b32 v0, v158 offset:34816
	global_load_dwordx2 v[92:93], v[6:7], off offset:64
	global_load_dwordx2 v[90:91], v[6:7], off offset:80
	global_load_dwordx2 v[88:89], v[6:7], off offset:96
	global_load_dwordx2 v[86:87], v[6:7], off offset:112
	v_lshlrev_b32_e32 v6, 16, v54
	v_and_b32_e32 v7, 0xffff0000, v54
	v_and_b32_e32 v8, 0xffff0000, v55
	s_waitcnt lgkmcnt(0)
	v_mul_f32_e32 v6, v0, v6
	v_mul_f32_e32 v7, v0, v7
	v_mul_f32_e32 v6, v42, v6
	v_mul_f32_e32 v7, v43, v7
	v_cvt_pk_bf16_f32 v6, v6, v7
	v_lshlrev_b32_e32 v7, 16, v55
	v_mul_f32_e32 v7, v0, v7
	v_mul_f32_e32 v8, v0, v8
	v_mul_f32_e32 v7, v44, v7
	v_mul_f32_e32 v8, v45, v8
	v_cvt_pk_bf16_f32 v7, v7, v8
	v_lshlrev_b32_e32 v8, 16, v56
	v_and_b32_e32 v9, 0xffff0000, v56
	v_mul_f32_e32 v8, v0, v8
	v_mul_f32_e32 v9, v0, v9
	v_mul_f32_e32 v8, v34, v8
	v_mul_f32_e32 v9, v35, v9
	v_cvt_pk_bf16_f32 v8, v8, v9
	v_lshlrev_b32_e32 v9, 16, v57
	v_and_b32_e32 v10, 0xffff0000, v57
	v_mul_f32_e32 v9, v0, v9
	v_mul_f32_e32 v0, v0, v10
	v_mul_f32_e32 v0, v37, v0
	v_mul_f32_e32 v9, v36, v9
	v_cvt_pk_bf16_f32 v0, v9, v0
	ds_write_b16 v155, v6
	ds_write_b16_d16_hi v155, v6 offset:272
	ds_write_b16 v155, v7 offset:544
	ds_write_b16_d16_hi v155, v7 offset:816
	ds_write_b16 v155, v8 offset:1088
	ds_read_b32 v6, v159 offset:34816
	ds_write_b16_d16_hi v155, v8 offset:1360
	ds_write_b16 v155, v0 offset:1632
	ds_write_b16_d16_hi v155, v0 offset:1904
	v_lshlrev_b32_e32 v0, 16, v50
	v_and_b32_e32 v7, 0xffff0000, v50
	v_and_b32_e32 v8, 0xffff0000, v51
	s_waitcnt lgkmcnt(3)
	v_mul_f32_e32 v0, v6, v0
	v_mul_f32_e32 v7, v6, v7
	v_mul_f32_e32 v0, v42, v0
	v_mul_f32_e32 v7, v43, v7
	v_cvt_pk_bf16_f32 v0, v0, v7
	v_lshlrev_b32_e32 v7, 16, v51
	v_mul_f32_e32 v7, v6, v7
	v_mul_f32_e32 v8, v6, v8
	v_mul_f32_e32 v7, v44, v7
	v_mul_f32_e32 v8, v45, v8
	v_cvt_pk_bf16_f32 v7, v7, v8
	v_lshlrev_b32_e32 v8, 16, v52
	v_and_b32_e32 v9, 0xffff0000, v52
	v_mul_f32_e32 v8, v6, v8
	v_mul_f32_e32 v9, v6, v9
	v_mul_f32_e32 v8, v34, v8
	v_mul_f32_e32 v9, v35, v9
	v_cvt_pk_bf16_f32 v8, v8, v9
	v_lshlrev_b32_e32 v9, 16, v53
	v_and_b32_e32 v10, 0xffff0000, v53
	v_mul_f32_e32 v9, v6, v9
	v_mul_f32_e32 v6, v6, v10
	v_mul_f32_e32 v6, v37, v6
	v_mul_f32_e32 v9, v36, v9
	v_cvt_pk_bf16_f32 v6, v9, v6
	ds_write_b16 v156, v0
	ds_write_b16_d16_hi v156, v0 offset:272
	ds_write_b16 v156, v7 offset:544
	ds_write_b16_d16_hi v156, v7 offset:816
	ds_write_b16 v156, v8 offset:1088
	ds_read_b32 v0, v161 offset:34816
	ds_write_b16_d16_hi v156, v8 offset:1360
	ds_write_b16 v156, v6 offset:1632
	ds_write_b16_d16_hi v156, v6 offset:1904
	v_lshlrev_b32_e32 v6, 16, v46
	v_and_b32_e32 v7, 0xffff0000, v46
	v_and_b32_e32 v8, 0xffff0000, v47
	s_waitcnt lgkmcnt(3)
	v_mul_f32_e32 v6, v0, v6
	v_mul_f32_e32 v7, v0, v7
	v_mul_f32_e32 v6, v42, v6
	v_mul_f32_e32 v7, v43, v7
	v_cvt_pk_bf16_f32 v6, v6, v7
	v_lshlrev_b32_e32 v7, 16, v47
	v_mul_f32_e32 v7, v0, v7
	v_mul_f32_e32 v8, v0, v8
	v_mul_f32_e32 v7, v44, v7
	v_mul_f32_e32 v8, v45, v8
	v_cvt_pk_bf16_f32 v7, v7, v8
	v_lshlrev_b32_e32 v8, 16, v48
	v_and_b32_e32 v9, 0xffff0000, v48
	v_mul_f32_e32 v8, v0, v8
	v_mul_f32_e32 v9, v0, v9
	v_mul_f32_e32 v8, v34, v8
	v_mul_f32_e32 v9, v35, v9
	v_cvt_pk_bf16_f32 v8, v8, v9
	v_lshlrev_b32_e32 v9, 16, v49
	v_and_b32_e32 v10, 0xffff0000, v49
	v_mul_f32_e32 v9, v0, v9
	v_mul_f32_e32 v0, v0, v10
	v_mul_f32_e32 v0, v37, v0
	v_mul_f32_e32 v9, v36, v9
	v_cvt_pk_bf16_f32 v0, v9, v0
	ds_write_b16 v157, v6
	ds_write_b16_d16_hi v157, v6 offset:272
	ds_write_b16 v157, v7 offset:544
	ds_write_b16_d16_hi v157, v7 offset:816
	ds_write_b16 v157, v8 offset:1088
	ds_read_b32 v6, v162 offset:34816
	ds_write_b16_d16_hi v157, v8 offset:1360
	ds_write_b16 v157, v0 offset:1632
	ds_write_b16_d16_hi v157, v0 offset:1904
	v_lshlrev_b32_e32 v0, 16, v38
	v_and_b32_e32 v7, 0xffff0000, v38
	v_and_b32_e32 v8, 0xffff0000, v39
	s_waitcnt lgkmcnt(3)
	v_mul_f32_e32 v0, v6, v0
	v_mul_f32_e32 v7, v6, v7
	v_mul_f32_e32 v0, v42, v0
	v_mul_f32_e32 v7, v43, v7
	v_cvt_pk_bf16_f32 v0, v0, v7
	v_lshlrev_b32_e32 v7, 16, v39
	v_mul_f32_e32 v7, v6, v7
	v_mul_f32_e32 v8, v6, v8
	v_mul_f32_e32 v7, v44, v7
	v_mul_f32_e32 v8, v45, v8
	v_cvt_pk_bf16_f32 v7, v7, v8
	v_lshlrev_b32_e32 v8, 16, v40
	v_and_b32_e32 v9, 0xffff0000, v40
	v_mul_f32_e32 v8, v6, v8
	v_mul_f32_e32 v9, v6, v9
	v_mul_f32_e32 v8, v34, v8
	v_mul_f32_e32 v9, v35, v9
	v_cvt_pk_bf16_f32 v8, v8, v9
	v_lshlrev_b32_e32 v9, 16, v41
	v_and_b32_e32 v10, 0xffff0000, v41
	v_mul_f32_e32 v9, v6, v9
	v_mul_f32_e32 v6, v6, v10
	s_mov_b32 s10, s22
	v_mul_f32_e32 v6, v37, v6
	s_and_b64 vcc, exec, s[8:9]
	v_mul_f32_e32 v9, v36, v9
	v_cvt_pk_bf16_f32 v6, v9, v6
	ds_write_b16 v160, v0
	ds_write_b16_d16_hi v160, v0 offset:272
	ds_write_b16 v160, v7 offset:544
	ds_write_b16_d16_hi v160, v7 offset:816
	ds_write_b16 v160, v8 offset:1088
	ds_write_b16_d16_hi v160, v8 offset:1360
	ds_write_b16 v160, v6 offset:1632
	ds_write_b16_d16_hi v160, v6 offset:1904
	s_waitcnt lgkmcnt(0)
	s_barrier
	s_cbranch_vccnz .LBB0_675
	ds_read_b128 v[6:9], v245
	ds_read_b128 v[10:13], v247 offset:64
	s_waitcnt vmcnt(9) lgkmcnt(1)
	v_mfma_f32_32x32x16_bf16 v[18:33], v[6:9], v[2:5], 0
	s_waitcnt lgkmcnt(0)
	v_mfma_f32_32x32x16_bf16 v[2:17], v[10:13], v[2:5], 0
	s_and_b64 vcc, exec, s[8:9]
	s_cbranch_vccnz .LBB0_575
.LBB0_574:
	ds_read_b128 v[34:37], v246 offset:32
	s_waitcnt lgkmcnt(0)
	v_mfma_f32_32x32x16_bf16 v[18:33], v[34:37], v[82:85], v[18:33]
	ds_read_b128 v[34:37], v248 offset:96
	s_waitcnt lgkmcnt(0)
	v_mfma_f32_32x32x16_bf16 v[2:17], v[34:37], v[82:85], v[2:17]
.LBB0_575:
	s_and_b64 vcc, exec, s[6:7]
	s_cbranch_vccnz .LBB0_581
	ds_read_b128 v[34:37], v245 offset:64
	s_waitcnt lgkmcnt(0)
	v_mfma_f32_32x32x16_bf16 v[18:33], v[34:37], v[78:81], v[18:33]
	ds_read_b128 v[34:37], v247
	s_waitcnt lgkmcnt(0)
	v_mfma_f32_32x32x16_bf16 v[2:17], v[34:37], v[78:81], v[2:17]
	s_and_b64 vcc, exec, s[6:7]
	s_cbranch_vccz .LBB0_582

.LBB0_578:
	ds_read_b128 v[34:37], v245 offset:128
	s_waitcnt lgkmcnt(0)
	v_mfma_f32_32x32x16_bf16 v[18:33], v[34:37], v[70:73], v[18:33]
	ds_read_b128 v[34:37], v247 offset:192
	s_waitcnt lgkmcnt(0)
	v_mfma_f32_32x32x16_bf16 v[2:17], v[34:37], v[70:73], v[2:17]
	s_and_b64 vcc, exec, s[4:5]
	s_cbranch_vccz .LBB0_584

.LBB0_580:
	ds_read_b128 v[34:37], v245 offset:192
	s_waitcnt lgkmcnt(0)
	v_mfma_f32_32x32x16_bf16 v[18:33], v[34:37], v[62:65], v[18:33]
	ds_read_b128 v[34:37], v247 offset:128
	s_waitcnt lgkmcnt(0)
	v_mfma_f32_32x32x16_bf16 v[2:17], v[34:37], v[62:65], v[2:17]
	s_and_b64 vcc, exec, s[0:1]
	s_cbranch_vccz .LBB0_586
	s_branch .LBB0_587

.LBB0_582:
	ds_read_b128 v[34:37], v246 offset:96
	s_waitcnt lgkmcnt(0)
	v_mfma_f32_32x32x16_bf16 v[18:33], v[34:37], v[74:77], v[18:33]
	ds_read_b128 v[34:37], v248 offset:32
	s_waitcnt lgkmcnt(0)
	v_mfma_f32_32x32x16_bf16 v[2:17], v[34:37], v[74:77], v[2:17]
	s_and_b64 vcc, exec, s[4:5]
	s_cbranch_vccz .LBB0_578

.LBB0_584:
	ds_read_b128 v[34:37], v246 offset:160
	s_waitcnt lgkmcnt(0)
	v_mfma_f32_32x32x16_bf16 v[18:33], v[34:37], v[66:69], v[18:33]
	ds_read_b128 v[34:37], v248 offset:224
	s_waitcnt lgkmcnt(0)
	v_mfma_f32_32x32x16_bf16 v[2:17], v[34:37], v[66:69], v[2:17]
	s_and_b64 vcc, exec, s[0:1]
	s_cbranch_vccz .LBB0_580

.LBB0_586:
	ds_read_b128 v[34:37], v246 offset:224
	s_waitcnt lgkmcnt(0)
	v_mfma_f32_32x32x16_bf16 v[18:33], v[34:37], v[58:61], v[18:33]
	ds_read_b128 v[34:37], v248 offset:160
	s_waitcnt lgkmcnt(0)
	v_mfma_f32_32x32x16_bf16 v[2:17], v[34:37], v[58:61], v[2:17]
